# diff loop: split DMA wait, K waited at iteration end and V at a new mid-iteration barrier before PV
# baseline (speedup 1.0000x reference)
; #define MFMA(a, b, c) __builtin_amdgcn_mfma_f32_32x32x16_bf16((a), (b), (c), 0, 0, 0)
; DI void diff_pass(const bf16_t* __restrict__ qrow  , const bf16_t* __restrict__ kg, const bf16_t* __restrict__ vg,
;                   int nkt, int q0, float negM2, f32x16 (&O)[4], float& lsum, char* lds) {
;     ...
;             bf16x8 pf[4];
;             pf[0] = pack8(Sx[0], 0); pf[1] = pack8(Sx[0], 1); pf[2] = pack8(Sx[1], 0); pf[3] = pack8(Sx[1], 1);
;             {
;                 bf16x8 vf[2][4];
; #pragma unroll
;                 for (int db = 0; db < 4; ++db) vf[0][db] = *(const bf16x8*)(st + 8192 + (32 * db + l31) * 128 + ((h ^ f) << 4));
; #pragma unroll
;                 for (int s = 0; s < 4; ++s) {
;                     if (s < 3) {
; #pragma unroll
;                         for (int db = 0; db < 4; ++db) vf[(s + 1) & 1][db] = *(const bf16x8*)(st + 8192 + (32 * db + l31) * 128 + (((2 * (s + 1) + h) ^ f) << 4));
;                     }
; #pragma unroll
;                     for (int db = 0; db < 4; ++db) O[db] = MFMA(vf[s & 1][db], pf[s], O[db]);
;                     __builtin_amdgcn_sched_barrier(0);
;                 }
;             }
;         }
;         asm volatile("s_waitcnt vmcnt(0)" ::: "memory");
;         __syncthreads();
.LBB0_86:
	s_or_b64 exec, exec, s[30:31]
	s_waitcnt vmcnt(3)
	s_barrier
	ds_read_b128 v[114:117], v195 offset:8192
	ds_read_b128 v[122:125], v195 offset:12288
	v_cvt_pk_bf16_f32 v118, v2, v4
	v_cvt_pk_bf16_f32 v120, v10, v12
	ds_read_b128 v[196:199], v195 offset:16384
	v_cvt_pk_bf16_f32 v4, v11, v13
	ds_read_b128 v[10:13], v195 offset:20480
	v_cvt_pk_bf16_f32 v119, v6, v8
	v_cvt_pk_bf16_f32 v121, v14, v96
	v_cvt_pk_bf16_f32 v2, v3, v5
	v_cvt_pk_bf16_f32 v3, v7, v9
	s_waitcnt lgkmcnt(0)
	v_mfma_f32_32x32x16_bf16 v[80:95], v[114:117], v[118:121], v[80:95]
	v_cvt_pk_bf16_f32 v114, v100, v104
	v_cvt_pk_bf16_f32 v115, v98, v102
	v_cvt_pk_bf16_f32 v116, v106, v108
	v_cvt_pk_bf16_f32 v117, v112, v110
	v_cvt_pk_bf16_f32 v5, v15, v97
	v_cvt_pk_bf16_f32 v6, v101, v105
	v_cvt_pk_bf16_f32 v7, v99, v103
	v_mfma_f32_32x32x16_bf16 v[64:79], v[122:125], v[118:121], v[64:79]
	v_cvt_pk_bf16_f32 v8, v107, v109
	v_cvt_pk_bf16_f32 v9, v113, v111
	ds_read_b128 v[96:99], v194 offset:8192
	ds_read_b128 v[100:103], v194 offset:12288
	ds_read_b128 v[104:107], v194 offset:16384
	ds_read_b128 v[108:111], v194 offset:20480
	v_mfma_f32_32x32x16_bf16 v[48:63], v[196:199], v[118:121], v[48:63]
	v_mfma_f32_32x32x16_bf16 v[32:47], v[10:13], v[118:121], v[32:47]
	s_waitcnt lgkmcnt(0)
	v_mfma_f32_32x32x16_bf16 v[80:95], v[96:99], v[114:117], v[80:95]
	v_mfma_f32_32x32x16_bf16 v[64:79], v[100:103], v[114:117], v[64:79]
	v_mfma_f32_32x32x16_bf16 v[48:63], v[104:107], v[114:117], v[48:63]
	ds_read_b128 v[10:13], v193 offset:8192
	ds_read_b128 v[96:99], v193 offset:12288
	ds_read_b128 v[100:103], v193 offset:16384
	ds_read_b128 v[104:107], v193 offset:20480
	v_mfma_f32_32x32x16_bf16 v[32:47], v[108:111], v[114:117], v[32:47]
	s_waitcnt lgkmcnt(0)
	v_mfma_f32_32x32x16_bf16 v[80:95], v[10:13], v[2:5], v[80:95]
	v_mfma_f32_32x32x16_bf16 v[64:79], v[96:99], v[2:5], v[64:79]
	v_mfma_f32_32x32x16_bf16 v[48:63], v[100:103], v[2:5], v[48:63]
	ds_read_b128 v[10:13], v0 offset:8192
	ds_read_b128 v[96:99], v0 offset:12288
	ds_read_b128 v[100:103], v0 offset:16384
	ds_read_b128 v[108:111], v0 offset:20480
	v_mfma_f32_32x32x16_bf16 v[32:47], v[104:107], v[2:5], v[32:47]
	s_waitcnt lgkmcnt(0)
	v_mfma_f32_32x32x16_bf16 v[80:95], v[10:13], v[6:9], v[80:95]
	v_mfma_f32_32x32x16_bf16 v[64:79], v[96:99], v[6:9], v[64:79]
	v_mfma_f32_32x32x16_bf16 v[48:63], v[100:103], v[6:9], v[48:63]
	v_mfma_f32_32x32x16_bf16 v[32:47], v[108:111], v[6:9], v[32:47]
.LBB0_87:
	s_or_b64 exec, exec, s[28:29]
	s_waitcnt vmcnt(2)
	s_add_i32 s55, s55, 64
	s_add_i32 s54, s54, 1
	s_mov_b64 s[28:29], 0x10000
	v_lshl_add_u64 v[164:165], v[164:165], 0, s[18:19]
	s_cmp_eq_u32 s35, s55
	v_lshl_add_u64 v[160:161], v[160:161], 0, s[28:29]
	s_waitcnt vmcnt(2) lgkmcnt(0)
	s_barrier
	s_cbranch_scc1 .LBB0_93

; DI void diff_pass(const bf16_t* __restrict__ qrow  , const bf16_t* __restrict__ kg, const bf16_t* __restrict__ vg,
;                   int nkt, int q0, float negM2, f32x16 (&O)[4], float& lsum, char* lds) {
;     ...
;                 bf16x8 kf[2][4];
; #pragma unroll
;                 for (int kb = 0; kb < 2; ++kb)
; #pragma unroll
;                     for (int ks = 0; ks < 4; ++ks) kf[kb][ks] = *(const bf16x8*)(st + (32 * kb + l31) * 128 + (((2 * ks + h) ^ f) << 4));
;                 __builtin_amdgcn_sched_barrier(0);
; #pragma unroll
;                 for (int ks = 0; ks < 4; ++ks)
; #pragma unroll
;                     for (int kb = 0; kb < 2; ++kb) Sx[kb] = ks == 0 ? MFMA(kf[kb][0], qf[0], minit) : MFMA(kf[kb][ks], qf[ks], Sx[kb]);
;             }
;             if (kt * 64 + 63 > q0) {
; #pragma unroll
;                 for (int kb = 0; kb < 2; ++kb)
; #pragma unroll
;                     for (int i = 0; i < 16; ++i) {
;                         float p = fexp2(Sx[kb][i]);
;                         const int key = kt * 64 + 32 * kb + (i & 3) + 8 * (i >> 2) + 4 * h;
;                         if (key > qpos) p = 0.f;
;                         lsum += p; Sx[kb][i] = p;
;                     }
;             } else {
;                 float l0 = 0.f, l1 = 0.f;
; #pragma unroll
;                 for (int i = 0; i < 16; ++i) { const float p0 = fexp2(Sx[0][i]), p1 = fexp2(Sx[1][i]); l0 += p0; l1 += p1; Sx[0][i] = p0; Sx[1][i] = p1; }
;                 lsum += l0 + l1;
;             }
;             bf16x8 pf[4];
;             pf[0] = pack8(Sx[0], 0); pf[1] = pack8(Sx[0], 1); pf[2] = pack8(Sx[1], 0); pf[3] = pack8(Sx[1], 1);
;             {
;                 bf16x8 vf[2][4];
; #pragma unroll
;                 for (int db = 0; db < 4; ++db) vf[0][db] = *(const bf16x8*)(st + 8192 + (32 * db + l31) * 128 + ((h ^ f) << 4));
; #pragma unroll
;                 for (int s = 0; s < 4; ++s) {
;                     if (s < 3) {
; #pragma unroll
;                         for (int db = 0; db < 4; ++db) vf[(s + 1) & 1][db] = *(const bf16x8*)(st + 8192 + (32 * db + l31) * 128 + (((2 * (s + 1) + h) ^ f) << 4));
;                     }
; #pragma unroll
;                     for (int db = 0; db < 4; ++db) O[db] = MFMA(vf[s & 1][db], pf[s], O[db]);
;                     __builtin_amdgcn_sched_barrier(0);
;                 }
;             }
.Ldf_skipmid:
	s_waitcnt vmcnt(3)
	s_barrier
	s_branch .LBB0_87
.Ldf_fast:
	ds_read_b128 v[2:5], v195
	ds_read_b128 v[10:13], v194
	ds_read_b128 v[200:203], v193
	ds_read_b128 v[208:211], v0
	ds_read_b128 v[6:9], v195 offset:4096
	ds_read_b128 v[196:199], v194 offset:4096
	ds_read_b128 v[204:207], v193 offset:4096
	ds_read_b128 v[212:215], v0 offset:4096
	v_mov_b32_e32 v14, 0
	v_mov_b32_e32 v15, 0
	s_waitcnt lgkmcnt(7)
	v_mfma_f32_32x32x16_bf16 v[96:111], v[2:5], v[140:143], v[16:31]
	s_waitcnt lgkmcnt(6)
	v_mfma_f32_32x32x16_bf16 v[96:111], v[10:13], v[136:139], v[96:111]
	s_waitcnt lgkmcnt(5)
	v_mfma_f32_32x32x16_bf16 v[96:111], v[200:203], v[132:135], v[96:111]
	s_waitcnt lgkmcnt(4)
	v_mfma_f32_32x32x16_bf16 v[96:111], v[208:211], v[128:131], v[96:111]
	s_waitcnt lgkmcnt(3)
	v_mfma_f32_32x32x16_bf16 v[112:127], v[6:9], v[140:143], v[16:31]
	s_waitcnt lgkmcnt(2)
	v_mfma_f32_32x32x16_bf16 v[112:127], v[196:199], v[136:139], v[112:127]
	s_nop 3
	v_exp_f32_e32 v96, v96
	v_exp_f32_e32 v97, v97
	v_add_f32_e32 v14, v14, v96
	v_add_f32_e32 v14, v14, v97
	s_waitcnt lgkmcnt(1)
	v_mfma_f32_32x32x16_bf16 v[112:127], v[204:207], v[132:135], v[112:127]
	v_exp_f32_e32 v98, v98
	v_exp_f32_e32 v99, v99
	v_add_f32_e32 v14, v14, v98
	v_add_f32_e32 v14, v14, v99
	s_waitcnt lgkmcnt(0)
	v_mfma_f32_32x32x16_bf16 v[112:127], v[212:215], v[128:131], v[112:127]
	s_waitcnt vmcnt(3)
	s_barrier
	ds_read_b128 v[2:5], v195 offset:8192
	ds_read_b128 v[10:13], v195 offset:12288
	ds_read_b128 v[200:203], v195 offset:16384
	ds_read_b128 v[208:211], v195 offset:20480
	v_exp_f32_e32 v100, v100
	v_exp_f32_e32 v101, v101
	v_add_f32_e32 v14, v14, v100
	v_add_f32_e32 v14, v14, v101
	v_exp_f32_e32 v102, v102
	v_exp_f32_e32 v103, v103
	v_add_f32_e32 v14, v14, v102
	v_add_f32_e32 v14, v14, v103
	v_cvt_pk_bf16_f32 v96, v96, v97
	v_cvt_pk_bf16_f32 v97, v98, v99
	v_cvt_pk_bf16_f32 v98, v100, v101
	v_cvt_pk_bf16_f32 v99, v102, v103
	s_waitcnt lgkmcnt(3)
	s_nop 0
	v_mfma_f32_32x32x16_bf16 v[80:95], v[2:5], v[96:99], v[80:95]
	ds_read_b128 v[6:9], v194 offset:8192
	ds_read_b128 v[196:199], v194 offset:12288
	ds_read_b128 v[204:207], v194 offset:16384
	ds_read_b128 v[212:215], v194 offset:20480
	v_exp_f32_e32 v104, v104
	v_exp_f32_e32 v105, v105
	v_add_f32_e32 v14, v14, v104
	v_add_f32_e32 v14, v14, v105
	s_waitcnt lgkmcnt(6)
	v_mfma_f32_32x32x16_bf16 v[64:79], v[10:13], v[96:99], v[64:79]
	ds_read_b128 v[2:5], v193 offset:8192
	v_exp_f32_e32 v106, v106
	v_exp_f32_e32 v107, v107
	v_add_f32_e32 v14, v14, v106
	v_add_f32_e32 v14, v14, v107
	s_waitcnt lgkmcnt(6)
	v_mfma_f32_32x32x16_bf16 v[48:63], v[200:203], v[96:99], v[48:63]
	ds_read_b128 v[10:13], v193 offset:12288
	v_exp_f32_e32 v108, v108
	v_exp_f32_e32 v109, v109
	v_add_f32_e32 v14, v14, v108
	v_add_f32_e32 v14, v14, v109
	s_waitcnt lgkmcnt(6)
	v_mfma_f32_32x32x16_bf16 v[32:47], v[208:211], v[96:99], v[32:47]
	ds_read_b128 v[200:203], v193 offset:16384
	v_exp_f32_e32 v110, v110
	v_exp_f32_e32 v111, v111
	v_add_f32_e32 v14, v14, v110
	v_add_f32_e32 v14, v14, v111
	v_cvt_pk_bf16_f32 v104, v104, v105
	v_cvt_pk_bf16_f32 v105, v106, v107
	v_cvt_pk_bf16_f32 v106, v108, v109
	v_cvt_pk_bf16_f32 v107, v110, v111
	s_waitcnt lgkmcnt(6)
	s_nop 0
	v_mfma_f32_32x32x16_bf16 v[80:95], v[6:9], v[104:107], v[80:95]
	ds_read_b128 v[208:211], v193 offset:20480
	v_exp_f32_e32 v112, v112
	v_exp_f32_e32 v113, v113
	v_add_f32_e32 v15, v15, v112
	v_add_f32_e32 v15, v15, v113
	s_waitcnt lgkmcnt(6)
	v_mfma_f32_32x32x16_bf16 v[64:79], v[196:199], v[104:107], v[64:79]
	ds_read_b128 v[6:9], v0 offset:8192
	v_exp_f32_e32 v114, v114
	v_exp_f32_e32 v115, v115
	v_add_f32_e32 v15, v15, v114
	v_add_f32_e32 v15, v15, v115
	s_waitcnt lgkmcnt(6)
	v_mfma_f32_32x32x16_bf16 v[48:63], v[204:207], v[104:107], v[48:63]
	ds_read_b128 v[196:199], v0 offset:12288
	v_exp_f32_e32 v116, v116
	v_exp_f32_e32 v117, v117
	v_add_f32_e32 v15, v15, v116
	v_add_f32_e32 v15, v15, v117
	s_waitcnt lgkmcnt(6)
	v_mfma_f32_32x32x16_bf16 v[32:47], v[212:215], v[104:107], v[32:47]
	ds_read_b128 v[204:207], v0 offset:16384
	v_exp_f32_e32 v118, v118
	v_exp_f32_e32 v119, v119
	v_add_f32_e32 v15, v15, v118
	v_add_f32_e32 v15, v15, v119
	v_cvt_pk_bf16_f32 v112, v112, v113
	v_cvt_pk_bf16_f32 v113, v114, v115
	v_cvt_pk_bf16_f32 v114, v116, v117
	v_cvt_pk_bf16_f32 v115, v118, v119
	s_waitcnt lgkmcnt(6)
	s_nop 0
	v_mfma_f32_32x32x16_bf16 v[80:95], v[2:5], v[112:115], v[80:95]
	ds_read_b128 v[212:215], v0 offset:20480
	v_exp_f32_e32 v120, v120
	v_exp_f32_e32 v121, v121
	v_add_f32_e32 v15, v15, v120
	v_add_f32_e32 v15, v15, v121
	s_waitcnt lgkmcnt(6)
	v_mfma_f32_32x32x16_bf16 v[64:79], v[10:13], v[112:115], v[64:79]
	v_exp_f32_e32 v122, v122
	v_exp_f32_e32 v123, v123
	v_add_f32_e32 v15, v15, v122
	v_add_f32_e32 v15, v15, v123
	s_waitcnt lgkmcnt(5)
	v_mfma_f32_32x32x16_bf16 v[48:63], v[200:203], v[112:115], v[48:63]
	v_exp_f32_e32 v124, v124
	v_exp_f32_e32 v125, v125
	v_add_f32_e32 v15, v15, v124
	v_add_f32_e32 v15, v15, v125
	s_waitcnt lgkmcnt(4)
	v_mfma_f32_32x32x16_bf16 v[32:47], v[208:211], v[112:115], v[32:47]
	v_exp_f32_e32 v126, v126
	v_exp_f32_e32 v127, v127
	v_add_f32_e32 v15, v15, v126
	v_add_f32_e32 v15, v15, v127
	v_cvt_pk_bf16_f32 v120, v120, v121
	v_cvt_pk_bf16_f32 v121, v122, v123
	v_cvt_pk_bf16_f32 v122, v124, v125
	v_cvt_pk_bf16_f32 v123, v126, v127
	v_add_f32_e32 v14, v14, v15
	s_waitcnt lgkmcnt(3)
	v_mfma_f32_32x32x16_bf16 v[80:95], v[6:9], v[120:123], v[80:95]
	v_add_f32_e32 v186, v186, v14
	s_waitcnt lgkmcnt(2)
	v_mfma_f32_32x32x16_bf16 v[64:79], v[196:199], v[120:123], v[64:79]
	s_waitcnt lgkmcnt(1)
	v_mfma_f32_32x32x16_bf16 v[48:63], v[204:207], v[120:123], v[48:63]
	s_waitcnt lgkmcnt(0)
	v_mfma_f32_32x32x16_bf16 v[32:47], v[212:215], v[120:123], v[32:47]
	s_branch .LBB0_87
; #define MFMA(a, b, c) __builtin_amdgcn_mfma_f32_32x32x16_bf16((a), (b), (c), 0, 0, 0)
; DI float fexp2(float x) { return __builtin_amdgcn_exp2f(x); }
; DI void diff_pass(const bf16_t* __restrict__ qrow  , const bf16_t* __restrict__ kg, const bf16_t* __restrict__ vg,
;                   int nkt, int q0, float negM2, f32x16 (&O)[4], float& lsum, char* lds) {
;     ...
;         if (kt * 64 <= q0 + 31) {
;             f32x16 Sx[2];
;             {
;                 bf16x8 kf[2][4];
; #pragma unroll
;                 for (int kb = 0; kb < 2; ++kb)
; #pragma unroll
;                     for (int ks = 0; ks < 4; ++ks) kf[kb][ks] = *(const bf16x8*)(st + (32 * kb + l31) * 128 + (((2 * ks + h) ^ f) << 4));
;                 __builtin_amdgcn_sched_barrier(0);
; #pragma unroll
;                 for (int ks = 0; ks < 4; ++ks)
; #pragma unroll
;                     for (int kb = 0; kb < 2; ++kb) Sx[kb] = ks == 0 ? MFMA(kf[kb][0], qf[0], minit) : MFMA(kf[kb][ks], qf[ks], Sx[kb]);
;             }
;             if (kt * 64 + 63 > q0) {
; #pragma unroll
;                 for (int kb = 0; kb < 2; ++kb)
; #pragma unroll
;                     for (int i = 0; i < 16; ++i) {
;                         float p = fexp2(Sx[kb][i]);
;                         const int key = kt * 64 + 32 * kb + (i & 3) + 8 * (i >> 2) + 4 * h;
;                         if (key > qpos) p = 0.f;
;                         lsum += p; Sx[kb][i] = p;
;                     }
;             } else {
;                 float l0 = 0.f, l1 = 0.f;
; #pragma unroll
;                 for (int i = 0; i < 16; ++i) { const float p0 = fexp2(Sx[0][i]), p1 = fexp2(Sx[1][i]); l0 += p0; l1 += p1; Sx[0][i] = p0; Sx[1][i] = p1; }
;                 lsum += l0 + l1;
.LBB0_93:
	s_waitcnt vmcnt(0)
	s_barrier
	v_cmp_le_i32_e32 vcc, s35, v171
	s_and_saveexec_b64 s[28:29], vcc
	s_cbranch_execz .LBB0_99
	v_add_u32_e32 v160, v188, v189
	v_add_u32_e32 v159, v188, v190
	v_add_u32_e32 v158, v188, v191
	v_add_u32_e32 v0, v188, v192
	ds_read_b128 v[2:5], v160 offset:24576
	ds_read_b128 v[6:9], v160 offset:28672
	ds_read_b128 v[10:13], v159 offset:24576
	ds_read_b128 v[188:191], v159 offset:28672
	ds_read_b128 v[192:195], v158 offset:24576
	ds_read_b128 v[196:199], v158 offset:28672
	ds_read_b128 v[200:203], v0 offset:24576
	ds_read_b128 v[204:207], v0 offset:28672
	s_waitcnt lgkmcnt(7)
	v_mfma_f32_32x32x16_bf16 v[96:111], v[2:5], v[140:143], v[16:31]
	s_or_b32 s30, s35, 63
	v_cmp_le_i32_e32 vcc, s30, v148
	s_waitcnt lgkmcnt(6)
	v_mfma_f32_32x32x16_bf16 v[112:127], v[6:9], v[140:143], v[16:31]
	s_waitcnt lgkmcnt(5)
	v_mfma_f32_32x32x16_bf16 v[96:111], v[10:13], v[136:139], v[96:111]
	s_waitcnt lgkmcnt(4)
	v_mfma_f32_32x32x16_bf16 v[112:127], v[188:191], v[136:139], v[112:127]
	s_waitcnt lgkmcnt(3)
	v_mfma_f32_32x32x16_bf16 v[96:111], v[192:195], v[132:135], v[96:111]
	s_waitcnt lgkmcnt(2)
	v_mfma_f32_32x32x16_bf16 v[112:127], v[196:199], v[132:135], v[112:127]
	s_waitcnt lgkmcnt(1)
	v_mfma_f32_32x32x16_bf16 v[96:111], v[200:203], v[128:131], v[96:111]
	s_waitcnt lgkmcnt(0)
	v_mfma_f32_32x32x16_bf16 v[112:127], v[204:207], v[128:131], v[112:127]
	s_nop 9
	v_exp_f32_e32 v2, v96
	v_exp_f32_e32 v4, v97
	v_exp_f32_e32 v6, v98
	v_exp_f32_e32 v8, v99
	v_exp_f32_e32 v10, v100
	v_exp_f32_e32 v12, v101
	v_exp_f32_e32 v14, v102
	v_exp_f32_e32 v3, v112
	v_exp_f32_e32 v5, v113
	v_exp_f32_e32 v7, v114
	v_exp_f32_e32 v9, v115
	v_exp_f32_e32 v11, v116
	v_exp_f32_e32 v13, v117
	v_exp_f32_e32 v15, v118
	v_exp_f32_e32 v96, v103
	v_exp_f32_e32 v97, v119
	v_exp_f32_e32 v100, v104
	v_exp_f32_e32 v101, v120
	v_exp_f32_e32 v104, v105
	v_exp_f32_e32 v105, v121
	v_exp_f32_e32 v98, v106
	v_exp_f32_e32 v99, v122
	v_exp_f32_e32 v102, v107
	v_exp_f32_e32 v103, v123
	v_exp_f32_e32 v106, v108
	v_exp_f32_e32 v107, v124
	v_exp_f32_e32 v108, v109
	v_exp_f32_e32 v109, v125
	v_exp_f32_e32 v112, v110
	v_exp_f32_e32 v113, v126
	v_exp_f32_e32 v110, v111
	v_exp_f32_e32 v111, v127
	s_and_saveexec_b64 s[30:31], vcc
	s_xor_b64 s[30:31], exec, s[30:31]
	s_cbranch_execz .LBB0_96
	v_pk_add_f32 v[114:115], v[2:3], 0 op_sel_hi:[1,0]
	s_nop 0
	v_pk_add_f32 v[114:115], v[4:5], v[114:115]
	s_nop 0
	v_pk_add_f32 v[114:115], v[6:7], v[114:115]
	s_nop 0
	v_pk_add_f32 v[114:115], v[8:9], v[114:115]
	s_nop 0
	v_pk_add_f32 v[114:115], v[10:11], v[114:115]
	s_nop 0
	v_pk_add_f32 v[114:115], v[12:13], v[114:115]
	s_nop 0
	v_pk_add_f32 v[114:115], v[14:15], v[114:115]
	s_nop 0
	v_pk_add_f32 v[114:115], v[96:97], v[114:115]
	s_nop 0
	v_pk_add_f32 v[114:115], v[100:101], v[114:115]
	s_nop 0
	v_pk_add_f32 v[114:115], v[104:105], v[114:115]
	s_nop 0
	v_pk_add_f32 v[114:115], v[98:99], v[114:115]
	s_nop 0
	v_pk_add_f32 v[114:115], v[102:103], v[114:115]
	s_nop 0
	v_pk_add_f32 v[114:115], v[106:107], v[114:115]
	s_nop 0
	v_pk_add_f32 v[114:115], v[108:109], v[114:115]
	s_nop 0
	v_pk_add_f32 v[114:115], v[112:113], v[114:115]
	s_nop 0
	v_pk_add_f32 v[114:115], v[110:111], v[114:115]
	s_nop 0
	v_add_f32_e32 v114, v114, v115
	v_add_f32_e32 v114, v186, v114
